# last phase: the input x rows (read once, cold) are loaded with the nt hint like in the first phase
# speedup vs baseline: 1.0106x; 1.0019x over previous
.LBB0_28:
	v_add_u32_e32 v210, -3, v86
	v_ashrrev_i32_e32 v211, 31, v210
	v_lshlrev_b64 v[210:211], 11, v[210:211]
	v_lshl_add_u64 v[210:211], v[206:207], 0, v[210:211]
	global_load_dwordx2 v[142:143], v[210:211], off
	global_load_dwordx2 v[144:145], v[210:211], off offset:512
	global_load_dwordx2 v[146:147], v[210:211], off offset:1024
	global_load_dwordx2 v[148:149], v[210:211], off offset:1536
	v_add_u32_e32 v210, -2, v86
	v_ashrrev_i32_e32 v211, 31, v210
	v_lshlrev_b64 v[210:211], 11, v[210:211]
	v_lshl_add_u64 v[210:211], v[206:207], 0, v[210:211]
	global_load_dwordx2 v[150:151], v[210:211], off
	global_load_dwordx2 v[152:153], v[210:211], off offset:512
	global_load_dwordx2 v[154:155], v[210:211], off offset:1024
	global_load_dwordx2 v[156:157], v[210:211], off offset:1536
	v_add_u32_e32 v210, -1, v86
	v_ashrrev_i32_e32 v211, 31, v210
	v_lshlrev_b64 v[210:211], 11, v[210:211]
	v_lshl_add_u64 v[210:211], v[206:207], 0, v[210:211]
	global_load_dwordx2 v[158:159], v[210:211], off
	global_load_dwordx2 v[160:161], v[210:211], off offset:512
	global_load_dwordx2 v[162:163], v[210:211], off offset:1024
	global_load_dwordx2 v[164:165], v[210:211], off offset:1536
	v_add_u32_e32 v210, 0, v86
	v_ashrrev_i32_e32 v211, 31, v210
	v_lshlrev_b64 v[210:211], 11, v[210:211]
	v_lshl_add_u64 v[210:211], v[206:207], 0, v[210:211]
	global_load_dwordx2 v[166:167], v[210:211], off
	global_load_dwordx2 v[168:169], v[210:211], off offset:512
	global_load_dwordx2 v[170:171], v[210:211], off offset:1024
	global_load_dwordx2 v[172:173], v[210:211], off offset:1536
	v_add_u32_e32 v18, -3, v86
	v_ashrrev_i32_e32 v19, 31, v18
	v_lshlrev_b64 v[20:21], 12, v[18:19]
	v_lshl_add_u64 v[104:105], v[82:83], 0, v[20:21]
	v_lshlrev_b64 v[18:19], 11, v[18:19]
	v_lshl_add_u64 v[18:19], v[84:85], 0, v[18:19]
	v_lshl_add_u64 v[208:209], v[104:105], 0, s[66:67]
	global_load_dwordx4 v[78:81], v[208:209], off nt
	global_load_dwordx2 v[122:123], v[18:19], off
	global_load_dwordx4 v[74:77], v[208:209], off offset:1024 nt
	global_load_dwordx2 v[124:125], v[18:19], off offset:512
	global_load_dwordx4 v[70:73], v[208:209], off offset:2048 nt
	global_load_dwordx2 v[126:127], v[18:19], off offset:1024
	global_load_dwordx4 v[66:69], v[208:209], off offset:3072 nt
	global_load_dwordx2 v[128:129], v[18:19], off offset:1536
	v_add_u32_e32 v18, -2, v86
	v_ashrrev_i32_e32 v19, 31, v18
	v_lshlrev_b64 v[20:21], 12, v[18:19]
	v_lshl_add_u64 v[94:95], v[82:83], 0, v[20:21]
	v_lshlrev_b64 v[18:19], 11, v[18:19]
	v_lshl_add_u64 v[18:19], v[84:85], 0, v[18:19]
	v_lshl_add_u64 v[208:209], v[94:95], 0, s[66:67]
	global_load_dwordx4 v[62:65], v[208:209], off nt
	global_load_dwordx2 v[118:119], v[18:19], off
	global_load_dwordx4 v[58:61], v[208:209], off offset:1024 nt
	global_load_dwordx2 v[116:117], v[18:19], off offset:512
	global_load_dwordx4 v[54:57], v[208:209], off offset:2048 nt
	global_load_dwordx2 v[114:115], v[18:19], off offset:1024
	global_load_dwordx4 v[50:53], v[208:209], off offset:3072 nt
	global_load_dwordx2 v[112:113], v[18:19], off offset:1536
	v_add_u32_e32 v18, -1, v86
	v_ashrrev_i32_e32 v19, 31, v18
	v_lshlrev_b64 v[20:21], 12, v[18:19]
	v_lshlrev_b64 v[18:19], 11, v[18:19]
	v_lshl_add_u64 v[90:91], v[82:83], 0, v[20:21]
	v_lshl_add_u64 v[18:19], v[84:85], 0, v[18:19]
	v_ashrrev_i32_e32 v87, 31, v86
	v_lshl_add_u64 v[208:209], v[90:91], 0, s[66:67]
	global_load_dwordx4 v[46:49], v[208:209], off nt
	global_load_dwordx2 v[110:111], v[18:19], off
	global_load_dwordx4 v[42:45], v[208:209], off offset:1024 nt
	global_load_dwordx2 v[108:109], v[18:19], off offset:512
	global_load_dwordx4 v[38:41], v[208:209], off offset:2048 nt
	global_load_dwordx2 v[106:107], v[18:19], off offset:1024
	global_load_dwordx4 v[34:37], v[208:209], off offset:3072 nt
	global_load_dwordx2 v[102:103], v[18:19], off offset:1536
	v_lshlrev_b64 v[18:19], 12, v[86:87]
	v_lshl_add_u64 v[88:89], v[82:83], 0, v[18:19]
	v_lshlrev_b64 v[18:19], 11, v[86:87]
	v_lshl_add_u64 v[92:93], v[84:85], 0, v[18:19]
	v_lshl_add_u64 v[208:209], v[88:89], 0, s[66:67]
	global_load_dwordx4 v[30:33], v[208:209], off nt
	global_load_dwordx2 v[100:101], v[92:93], off
	global_load_dwordx4 v[26:29], v[208:209], off offset:1024 nt
	global_load_dwordx2 v[98:99], v[92:93], off offset:512
	global_load_dwordx4 v[22:25], v[208:209], off offset:2048 nt
	global_load_dwordx2 v[96:97], v[92:93], off offset:1024
	global_load_dwordx4 v[18:21], v[208:209], off offset:3072 nt
	s_nop 0
	global_load_dwordx2 v[92:93], v[92:93], off offset:1536
	v_add_u32_e32 v120, s3, v120
	v_add_u32_e32 v86, s3, v86
	s_waitcnt vmcnt(30)
	v_lshlrev_b32_e32 v0, 16, v142
	v_and_b32_e32 v87, 0xffff0000, v142
	v_and_b32_e32 v142, 0xffff0000, v143
	v_lshlrev_b32_e32 v121, 16, v143
	v_mul_f32_e32 v143, v87, v87
	v_mul_f32_e32 v130, v142, v142
	v_fmac_f32_e32 v143, v0, v0
	v_fmac_f32_e32 v130, v121, v121
	v_add_f32_e32 v143, v143, v130
	s_waitcnt vmcnt(28)
	v_lshlrev_b32_e32 v130, 16, v144
	v_and_b32_e32 v144, 0xffff0000, v144
	v_lshlrev_b32_e32 v131, 16, v145
	v_and_b32_e32 v145, 0xffff0000, v145
	v_mul_f32_e32 v132, v144, v144
	v_mul_f32_e32 v133, v145, v145
	v_fmac_f32_e32 v132, v130, v130
	v_fmac_f32_e32 v133, v131, v131
	v_add_f32_e32 v132, v132, v133
	v_add_f32_e32 v143, v143, v132
	s_waitcnt vmcnt(26)
	v_lshlrev_b32_e32 v132, 16, v146
	v_and_b32_e32 v146, 0xffff0000, v146
	v_lshlrev_b32_e32 v133, 16, v147
	v_and_b32_e32 v147, 0xffff0000, v147
	v_mul_f32_e32 v134, v146, v146
	v_mul_f32_e32 v135, v147, v147
	v_fmac_f32_e32 v134, v132, v132
	v_fmac_f32_e32 v135, v133, v133
	v_add_f32_e32 v134, v134, v135
	v_add_f32_e32 v143, v143, v134
	s_waitcnt vmcnt(24)
	v_lshlrev_b32_e32 v134, 16, v148
	v_and_b32_e32 v148, 0xffff0000, v148
	v_lshlrev_b32_e32 v135, 16, v149
	v_and_b32_e32 v149, 0xffff0000, v149
	v_mul_f32_e32 v136, v148, v148
	v_mul_f32_e32 v137, v149, v149
	v_fmac_f32_e32 v136, v134, v134
	v_fmac_f32_e32 v137, v135, v135
	v_add_f32_e32 v136, v136, v137
	v_add_f32_e32 v143, v143, v136
	s_nop 1
	v_add_f32_dpp v143, v143, v143 quad_perm:[1,0,3,2] row_mask:0xf bank_mask:0xf bound_ctrl:1
	s_nop 1
	v_add_f32_dpp v143, v143, v143 quad_perm:[2,3,0,1] row_mask:0xf bank_mask:0xf bound_ctrl:1
	s_nop 1
	v_add_f32_dpp v143, v143, v143 row_half_mirror row_mask:0xf bank_mask:0xf bound_ctrl:1
	s_nop 1
	v_add_f32_dpp v143, v143, v143 row_mirror row_mask:0xf bank_mask:0xf bound_ctrl:1
	s_nop 0
	v_readlane_b32 s1, v143, 16
	v_readlane_b32 s6, v143, 48
	v_readlane_b32 s0, v143, 0
	v_readlane_b32 s2, v143, 32
	v_mov_b32_e32 v143, s1
	v_mov_b32_e32 v136, s6
	v_add_f32_e32 v143, s0, v143
	v_add_f32_e32 v136, s2, v136
	v_add_f32_e32 v143, v143, v136
	v_fmamk_f32 v143, v143, 0x3a800000, v188
	v_cmp_gt_f32_e32 vcc, s49, v143
	v_mul_f32_e32 v136, 0x4f800000, v143
	s_nop 0
	v_cndmask_b32_e32 v143, v143, v136, vcc
	v_sqrt_f32_e32 v136, v143
	s_nop 0
	v_add_u32_e32 v137, -1, v136
	v_fma_f32 v138, -v137, v136, v143
	v_cmp_ge_f32_e64 s[0:1], 0, v138
	v_add_u32_e32 v138, 1, v136
	s_nop 0
	v_cndmask_b32_e64 v137, v136, v137, s[0:1]
	v_fma_f32 v136, -v138, v136, v143
	v_cmp_lt_f32_e64 s[0:1], 0, v136
	s_nop 1
	v_cndmask_b32_e64 v136, v137, v138, s[0:1]
	v_mul_f32_e32 v137, 0x37800000, v136
	v_cndmask_b32_e32 v136, v136, v137, vcc
	v_cmp_class_f32_e32 vcc, v143, v189
	s_nop 1
	v_cndmask_b32_e32 v143, v136, v143, vcc
	v_div_scale_f32 v136, s[0:1], v143, v143, 1.0
	v_rcp_f32_e32 v137, v136
	s_nop 0
	v_fma_f32 v138, -v136, v137, 1.0
	v_fmac_f32_e32 v137, v138, v137
	v_div_scale_f32 v138, vcc, 1.0, v143, 1.0
	v_mul_f32_e32 v139, v138, v137
	v_fma_f32 v140, -v136, v139, v138
	v_fmac_f32_e32 v139, v140, v137
	v_fma_f32 v136, -v136, v139, v138
	v_div_fmas_f32 v136, v136, v137, v139
	v_div_fixup_f32 v143, v136, v143, 1.0
	v_mul_f32_e32 v0, v0, v143
	v_mul_f32_e32 v87, v87, v143
	v_mul_f32_e32 v121, v121, v143
	v_mul_f32_e32 v142, v142, v143
	v_fma_f32 v81, v191, v142, v81
	v_fma_f32 v80, v190, v121, v80
	v_fma_f32 v79, v193, v87, v79
	v_fmac_f32_e32 v78, v192, v0
	v_mul_f32_e32 v0, v130, v143
	v_fmac_f32_e32 v74, v196, v0
	v_mul_f32_e32 v212, v144, v143
	v_mul_f32_e32 v213, v131, v143
	v_mul_f32_e32 v214, v145, v143
	v_fma_f32 v77, v195, v214, v77
	v_fma_f32 v76, v194, v213, v76
	v_fma_f32 v75, v197, v212, v75
	v_mul_f32_e32 v0, v132, v143
	v_fmac_f32_e32 v70, v200, v0
	v_mul_f32_e32 v216, v146, v143
	v_mul_f32_e32 v217, v133, v143
	v_mul_f32_e32 v218, v147, v143
	v_fma_f32 v73, v199, v218, v73
	v_fma_f32 v72, v198, v217, v72
	v_fma_f32 v71, v201, v216, v71
	v_mul_f32_e32 v0, v134, v143
	v_fmac_f32_e32 v66, v204, v0
	v_mul_f32_e32 v220, v148, v143
	v_mul_f32_e32 v221, v135, v143
	v_mul_f32_e32 v222, v149, v143
	v_fma_f32 v69, v203, v222, v69
	v_fma_f32 v68, v202, v221, v68
	v_fma_f32 v67, v205, v220, v67
	s_waitcnt vmcnt(30)
	v_lshlrev_b32_e32 v0, 16, v122
	v_and_b32_e32 v87, 0xffff0000, v122
	v_and_b32_e32 v122, 0xffff0000, v123
	v_lshlrev_b32_e32 v121, 16, v123
	v_mul_f32_e32 v123, v87, v87
	v_mul_f32_e32 v130, v122, v122
	v_fmac_f32_e32 v123, v0, v0
	v_fmac_f32_e32 v130, v121, v121
	v_add_f32_e32 v123, v123, v130
	s_waitcnt vmcnt(28)
	v_lshlrev_b32_e32 v130, 16, v124
	v_and_b32_e32 v124, 0xffff0000, v124
	v_lshlrev_b32_e32 v131, 16, v125
	v_and_b32_e32 v125, 0xffff0000, v125
	v_mul_f32_e32 v132, v124, v124
	v_mul_f32_e32 v133, v125, v125
	v_fmac_f32_e32 v132, v130, v130
	v_fmac_f32_e32 v133, v131, v131
	v_add_f32_e32 v132, v132, v133
	v_add_f32_e32 v123, v123, v132
	s_waitcnt vmcnt(26)
	v_lshlrev_b32_e32 v132, 16, v126
	v_and_b32_e32 v126, 0xffff0000, v126
	v_lshlrev_b32_e32 v133, 16, v127
	v_and_b32_e32 v127, 0xffff0000, v127
	v_mul_f32_e32 v134, v126, v126
	v_mul_f32_e32 v135, v127, v127
	v_fmac_f32_e32 v134, v132, v132
	v_fmac_f32_e32 v135, v133, v133
	v_add_f32_e32 v134, v134, v135
	v_add_f32_e32 v123, v123, v134
	s_waitcnt vmcnt(24)
	v_lshlrev_b32_e32 v134, 16, v128
	v_and_b32_e32 v128, 0xffff0000, v128
	v_lshlrev_b32_e32 v135, 16, v129
	v_and_b32_e32 v129, 0xffff0000, v129
	v_mul_f32_e32 v136, v128, v128
	v_mul_f32_e32 v137, v129, v129
	v_fmac_f32_e32 v136, v134, v134
	v_fmac_f32_e32 v137, v135, v135
	v_add_f32_e32 v136, v136, v137
	v_add_f32_e32 v123, v123, v136
	s_nop 1
	v_add_f32_dpp v123, v123, v123 quad_perm:[1,0,3,2] row_mask:0xf bank_mask:0xf bound_ctrl:1
	s_nop 1
	v_add_f32_dpp v123, v123, v123 quad_perm:[2,3,0,1] row_mask:0xf bank_mask:0xf bound_ctrl:1
	s_nop 1
	v_add_f32_dpp v123, v123, v123 row_half_mirror row_mask:0xf bank_mask:0xf bound_ctrl:1
	s_nop 1
	v_add_f32_dpp v123, v123, v123 row_mirror row_mask:0xf bank_mask:0xf bound_ctrl:1
	s_nop 0
	v_readlane_b32 s1, v123, 16
	v_readlane_b32 s6, v123, 48
	v_readlane_b32 s0, v123, 0
	v_readlane_b32 s2, v123, 32
	v_mov_b32_e32 v123, s1
	v_mov_b32_e32 v136, s6
	v_add_f32_e32 v123, s0, v123
	v_add_f32_e32 v136, s2, v136
	v_add_f32_e32 v123, v123, v136
	v_fmamk_f32 v123, v123, 0x3a800000, v188
	v_cmp_gt_f32_e32 vcc, s49, v123
	v_mul_f32_e32 v136, 0x4f800000, v123
	s_nop 0
	v_cndmask_b32_e32 v123, v123, v136, vcc
	v_sqrt_f32_e32 v136, v123
	s_nop 0
	v_add_u32_e32 v137, -1, v136
	v_fma_f32 v138, -v137, v136, v123
	v_cmp_ge_f32_e64 s[0:1], 0, v138
	v_add_u32_e32 v138, 1, v136
	s_nop 0
	v_cndmask_b32_e64 v137, v136, v137, s[0:1]
	v_fma_f32 v136, -v138, v136, v123
	v_cmp_lt_f32_e64 s[0:1], 0, v136
	s_nop 1
	v_cndmask_b32_e64 v136, v137, v138, s[0:1]
	v_mul_f32_e32 v137, 0x37800000, v136
	v_cndmask_b32_e32 v136, v136, v137, vcc
	v_cmp_class_f32_e32 vcc, v123, v189
	s_nop 1
	v_cndmask_b32_e32 v123, v136, v123, vcc
	v_div_scale_f32 v136, s[0:1], v123, v123, 1.0
	v_rcp_f32_e32 v137, v136
	s_nop 0
	v_fma_f32 v138, -v136, v137, 1.0
	v_fmac_f32_e32 v137, v138, v137
	v_div_scale_f32 v138, vcc, 1.0, v123, 1.0
	v_mul_f32_e32 v139, v138, v137
	v_fma_f32 v140, -v136, v139, v138
	v_fmac_f32_e32 v139, v140, v137
	v_fma_f32 v136, -v136, v139, v138
	v_div_fmas_f32 v136, v136, v137, v139
	v_div_fixup_f32 v123, v136, v123, 1.0
	v_mul_f32_e32 v0, v0, v123
	v_mul_f32_e32 v87, v87, v123
	v_mul_f32_e32 v121, v121, v123
	v_mul_f32_e32 v122, v122, v123
	v_fma_f32 v81, v3, v122, v81
	v_fma_f32 v80, v2, v121, v80
	v_fma_f32 v79, v5, v87, v79
	v_fmac_f32_e32 v78, v4, v0
	global_store_dwordx4 v[104:105], v[78:81], off nt
	v_mul_f32_e32 v0, v130, v123
	v_fmac_f32_e32 v74, v8, v0
	v_mul_f32_e32 v78, v124, v123
	v_mul_f32_e32 v79, v131, v123
	v_mul_f32_e32 v80, v125, v123
	v_fma_f32 v77, v7, v80, v77
	v_fma_f32 v76, v6, v79, v76
	v_fma_f32 v75, v9, v78, v75
	global_store_dwordx4 v[104:105], v[74:77], off offset:1024 nt
	v_mul_f32_e32 v0, v132, v123
	v_fmac_f32_e32 v70, v12, v0
	v_mul_f32_e32 v74, v126, v123
	v_mul_f32_e32 v75, v133, v123
	v_mul_f32_e32 v76, v127, v123
	v_fma_f32 v73, v11, v76, v73
	v_fma_f32 v72, v10, v75, v72
	v_fma_f32 v71, v13, v74, v71
	global_store_dwordx4 v[104:105], v[70:73], off offset:2048 nt
	v_mul_f32_e32 v0, v134, v123
	v_fmac_f32_e32 v66, v16, v0
	v_mul_f32_e32 v70, v128, v123
	v_mul_f32_e32 v71, v135, v123
	v_mul_f32_e32 v72, v129, v123
	v_fma_f32 v69, v15, v72, v69
	v_fma_f32 v68, v14, v71, v68
	v_fma_f32 v67, v17, v70, v67
	global_store_dwordx4 v[104:105], v[66:69], off offset:3072 nt
	s_waitcnt vmcnt(26)
	v_lshlrev_b32_e32 v0, 16, v150
	s_waitcnt vmcnt(24)
	v_and_b32_e32 v71, 0xffff0000, v152
	v_and_b32_e32 v66, 0xffff0000, v150
	v_and_b32_e32 v68, 0xffff0000, v151
	v_lshlrev_b32_e32 v67, 16, v151
	v_mul_f32_e32 v69, v66, v66
	v_mul_f32_e32 v70, v68, v68
	v_fmac_f32_e32 v69, v0, v0
	v_fmac_f32_e32 v70, v67, v67
	v_and_b32_e32 v73, 0xffff0000, v153
	v_add_f32_e32 v69, v69, v70
	v_lshlrev_b32_e32 v70, 16, v152
	v_lshlrev_b32_e32 v72, 16, v153
	v_mul_f32_e32 v74, v71, v71
	v_mul_f32_e32 v75, v73, v73
	v_fmac_f32_e32 v74, v70, v70
	v_fmac_f32_e32 v75, v72, v72
	v_add_f32_e32 v74, v74, v75
	s_waitcnt vmcnt(22)
	v_and_b32_e32 v75, 0xffff0000, v154
	v_and_b32_e32 v77, 0xffff0000, v155
	v_add_f32_e32 v69, v69, v74
	v_lshlrev_b32_e32 v74, 16, v154
	v_lshlrev_b32_e32 v76, 16, v155
	v_mul_f32_e32 v78, v75, v75
	v_mul_f32_e32 v79, v77, v77
	v_fmac_f32_e32 v78, v74, v74
	v_fmac_f32_e32 v79, v76, v76
	v_add_f32_e32 v78, v78, v79
	s_waitcnt vmcnt(20)
	v_and_b32_e32 v79, 0xffff0000, v156
	v_and_b32_e32 v81, 0xffff0000, v157
	v_add_f32_e32 v69, v69, v78
	v_lshlrev_b32_e32 v78, 16, v156
	v_lshlrev_b32_e32 v80, 16, v157
	v_mul_f32_e32 v87, v79, v79
	v_mul_f32_e32 v104, v81, v81
	v_fmac_f32_e32 v87, v78, v78
	v_fmac_f32_e32 v104, v80, v80
	v_add_f32_e32 v87, v87, v104
	v_add_f32_e32 v69, v69, v87
	s_nop 1
	v_add_f32_dpp v69, v69, v69 quad_perm:[1,0,3,2] row_mask:0xf bank_mask:0xf bound_ctrl:1
	s_nop 1
	v_add_f32_dpp v69, v69, v69 quad_perm:[2,3,0,1] row_mask:0xf bank_mask:0xf bound_ctrl:1
	s_nop 1
	v_add_f32_dpp v69, v69, v69 row_half_mirror row_mask:0xf bank_mask:0xf bound_ctrl:1
	s_nop 1
	v_add_f32_dpp v69, v69, v69 row_mirror row_mask:0xf bank_mask:0xf bound_ctrl:1
	s_nop 0
	v_readlane_b32 s1, v69, 16
	v_readlane_b32 s6, v69, 48
	v_readlane_b32 s0, v69, 0
	v_readlane_b32 s2, v69, 32
	v_mov_b32_e32 v69, s1
	v_mov_b32_e32 v87, s6
	v_add_f32_e32 v69, s0, v69
	v_add_f32_e32 v87, s2, v87
	v_add_f32_e32 v69, v69, v87
	v_fmamk_f32 v69, v69, 0x3a800000, v188
	v_cmp_gt_f32_e32 vcc, s49, v69
	v_mul_f32_e32 v87, 0x4f800000, v69
	s_nop 0
	v_cndmask_b32_e32 v69, v69, v87, vcc
	v_sqrt_f32_e32 v87, v69
	s_nop 0
	v_add_u32_e32 v104, -1, v87
	v_fma_f32 v105, -v104, v87, v69
	v_cmp_ge_f32_e64 s[0:1], 0, v105
	v_add_u32_e32 v105, 1, v87
	s_nop 0
	v_cndmask_b32_e64 v104, v87, v104, s[0:1]
	v_fma_f32 v87, -v105, v87, v69
	v_cmp_lt_f32_e64 s[0:1], 0, v87
	s_nop 1
	v_cndmask_b32_e64 v87, v104, v105, s[0:1]
	v_mul_f32_e32 v104, 0x37800000, v87
	v_cndmask_b32_e32 v87, v87, v104, vcc
	v_cmp_class_f32_e32 vcc, v69, v189
	s_nop 1
	v_cndmask_b32_e32 v69, v87, v69, vcc
	v_div_scale_f32 v87, s[0:1], v69, v69, 1.0
	v_rcp_f32_e32 v104, v87
	s_nop 0
	v_fma_f32 v105, -v87, v104, 1.0
	v_fmac_f32_e32 v104, v105, v104
	v_div_scale_f32 v105, vcc, 1.0, v69, 1.0
	v_mul_f32_e32 v156, v105, v104
	v_fma_f32 v157, -v87, v156, v105
	v_fmac_f32_e32 v156, v157, v104
	v_fma_f32 v87, -v87, v156, v105
	v_div_fmas_f32 v87, v87, v104, v156
	v_div_fixup_f32 v69, v87, v69, 1.0
	v_mul_f32_e32 v0, v0, v69
	v_mul_f32_e32 v66, v66, v69
	v_mul_f32_e32 v67, v67, v69
	v_mul_f32_e32 v68, v68, v69
	v_fma_f32 v65, v191, v68, v65
	v_fma_f32 v64, v190, v67, v64
	v_fma_f32 v63, v193, v66, v63
	v_fmac_f32_e32 v62, v192, v0
	v_mul_f32_e32 v0, v70, v69
	v_fmac_f32_e32 v58, v196, v0
	v_mul_f32_e32 v212, v71, v69
	v_mul_f32_e32 v213, v72, v69
	v_mul_f32_e32 v214, v73, v69
	v_fma_f32 v61, v195, v214, v61
	v_fma_f32 v60, v194, v213, v60
	v_fma_f32 v59, v197, v212, v59
	v_mul_f32_e32 v0, v74, v69
	v_fmac_f32_e32 v54, v200, v0
	v_mul_f32_e32 v216, v75, v69
	v_mul_f32_e32 v217, v76, v69
	v_mul_f32_e32 v218, v77, v69
	v_fma_f32 v57, v199, v218, v57
	v_fma_f32 v56, v198, v217, v56
	v_fma_f32 v55, v201, v216, v55
	v_mul_f32_e32 v0, v78, v69
	v_fmac_f32_e32 v50, v204, v0
	v_mul_f32_e32 v220, v79, v69
	v_mul_f32_e32 v221, v80, v69
	v_mul_f32_e32 v222, v81, v69
	v_fma_f32 v53, v203, v222, v53
	v_fma_f32 v52, v202, v221, v52
	v_fma_f32 v51, v205, v220, v51
	s_waitcnt vmcnt(26)
	v_lshlrev_b32_e32 v0, 16, v118
	s_waitcnt vmcnt(24)
	v_and_b32_e32 v71, 0xffff0000, v116
	v_and_b32_e32 v66, 0xffff0000, v118
	v_and_b32_e32 v68, 0xffff0000, v119
	v_lshlrev_b32_e32 v67, 16, v119
	v_mul_f32_e32 v69, v66, v66
	v_mul_f32_e32 v70, v68, v68
	v_fmac_f32_e32 v69, v0, v0
	v_fmac_f32_e32 v70, v67, v67
	v_and_b32_e32 v73, 0xffff0000, v117
	v_add_f32_e32 v69, v69, v70
	v_lshlrev_b32_e32 v70, 16, v116
	v_lshlrev_b32_e32 v72, 16, v117
	v_mul_f32_e32 v74, v71, v71
	v_mul_f32_e32 v75, v73, v73
	v_fmac_f32_e32 v74, v70, v70
	v_fmac_f32_e32 v75, v72, v72
	v_add_f32_e32 v74, v74, v75
	s_waitcnt vmcnt(22)
	v_and_b32_e32 v75, 0xffff0000, v114
	v_and_b32_e32 v77, 0xffff0000, v115
	v_add_f32_e32 v69, v69, v74
	v_lshlrev_b32_e32 v74, 16, v114
	v_lshlrev_b32_e32 v76, 16, v115
	v_mul_f32_e32 v78, v75, v75
	v_mul_f32_e32 v79, v77, v77
	v_fmac_f32_e32 v78, v74, v74
	v_fmac_f32_e32 v79, v76, v76
	v_add_f32_e32 v78, v78, v79
	s_waitcnt vmcnt(20)
	v_and_b32_e32 v79, 0xffff0000, v112
	v_and_b32_e32 v81, 0xffff0000, v113
	v_add_f32_e32 v69, v69, v78
	v_lshlrev_b32_e32 v78, 16, v112
	v_lshlrev_b32_e32 v80, 16, v113
	v_mul_f32_e32 v87, v79, v79
	v_mul_f32_e32 v104, v81, v81
	v_fmac_f32_e32 v87, v78, v78
	v_fmac_f32_e32 v104, v80, v80
	v_add_f32_e32 v87, v87, v104
	v_add_f32_e32 v69, v69, v87
	s_nop 1
	v_add_f32_dpp v69, v69, v69 quad_perm:[1,0,3,2] row_mask:0xf bank_mask:0xf bound_ctrl:1
	s_nop 1
	v_add_f32_dpp v69, v69, v69 quad_perm:[2,3,0,1] row_mask:0xf bank_mask:0xf bound_ctrl:1
	s_nop 1
	v_add_f32_dpp v69, v69, v69 row_half_mirror row_mask:0xf bank_mask:0xf bound_ctrl:1
	s_nop 1
	v_add_f32_dpp v69, v69, v69 row_mirror row_mask:0xf bank_mask:0xf bound_ctrl:1
	s_nop 0
	v_readlane_b32 s1, v69, 16
	v_readlane_b32 s6, v69, 48
	v_readlane_b32 s0, v69, 0
	v_readlane_b32 s2, v69, 32
	v_mov_b32_e32 v69, s1
	v_mov_b32_e32 v87, s6
	v_add_f32_e32 v69, s0, v69
	v_add_f32_e32 v87, s2, v87
	v_add_f32_e32 v69, v69, v87
	v_fmamk_f32 v69, v69, 0x3a800000, v188
	v_cmp_gt_f32_e32 vcc, s49, v69
	v_mul_f32_e32 v87, 0x4f800000, v69
	s_nop 0
	v_cndmask_b32_e32 v69, v69, v87, vcc
	v_sqrt_f32_e32 v87, v69
	s_nop 0
	v_add_u32_e32 v104, -1, v87
	v_fma_f32 v105, -v104, v87, v69
	v_cmp_ge_f32_e64 s[0:1], 0, v105
	v_add_u32_e32 v105, 1, v87
	s_nop 0
	v_cndmask_b32_e64 v104, v87, v104, s[0:1]
	v_fma_f32 v87, -v105, v87, v69
	v_cmp_lt_f32_e64 s[0:1], 0, v87
	s_nop 1
	v_cndmask_b32_e64 v87, v104, v105, s[0:1]
	v_mul_f32_e32 v104, 0x37800000, v87
	v_cndmask_b32_e32 v87, v87, v104, vcc
	v_cmp_class_f32_e32 vcc, v69, v189
	s_nop 1
	v_cndmask_b32_e32 v69, v87, v69, vcc
	v_div_scale_f32 v87, s[0:1], v69, v69, 1.0
	v_rcp_f32_e32 v104, v87
	s_nop 0
	v_fma_f32 v105, -v87, v104, 1.0
	v_fmac_f32_e32 v104, v105, v104
	v_div_scale_f32 v105, vcc, 1.0, v69, 1.0
	v_mul_f32_e32 v112, v105, v104
	v_fma_f32 v113, -v87, v112, v105
	v_fmac_f32_e32 v112, v113, v104
	v_fma_f32 v87, -v87, v112, v105
	v_div_fmas_f32 v87, v87, v104, v112
	v_div_fixup_f32 v69, v87, v69, 1.0
	v_mul_f32_e32 v0, v0, v69
	v_mul_f32_e32 v66, v66, v69
	v_mul_f32_e32 v67, v67, v69
	v_mul_f32_e32 v68, v68, v69
	v_fma_f32 v65, v3, v68, v65
	v_fma_f32 v64, v2, v67, v64
	v_fma_f32 v63, v5, v66, v63
	v_fmac_f32_e32 v62, v4, v0
	global_store_dwordx4 v[94:95], v[62:65], off nt
	v_mul_f32_e32 v0, v70, v69
	v_fmac_f32_e32 v58, v8, v0
	v_mul_f32_e32 v62, v71, v69
	v_mul_f32_e32 v63, v72, v69
	v_mul_f32_e32 v64, v73, v69
	v_fma_f32 v61, v7, v64, v61
	v_fma_f32 v60, v6, v63, v60
	v_fma_f32 v59, v9, v62, v59
	global_store_dwordx4 v[94:95], v[58:61], off offset:1024 nt
	v_mul_f32_e32 v0, v74, v69
	v_fmac_f32_e32 v54, v12, v0
	v_mul_f32_e32 v58, v75, v69
	v_mul_f32_e32 v59, v76, v69
	v_mul_f32_e32 v60, v77, v69
	v_fma_f32 v57, v11, v60, v57
	v_fma_f32 v56, v10, v59, v56
	v_fma_f32 v55, v13, v58, v55
	global_store_dwordx4 v[94:95], v[54:57], off offset:2048 nt
	v_mul_f32_e32 v0, v78, v69
	v_fmac_f32_e32 v50, v16, v0
	v_mul_f32_e32 v54, v79, v69
	v_mul_f32_e32 v55, v80, v69
	v_mul_f32_e32 v56, v81, v69
	v_fma_f32 v53, v15, v56, v53
	v_fma_f32 v52, v14, v55, v52
	v_fma_f32 v51, v17, v54, v51
	global_store_dwordx4 v[94:95], v[50:53], off offset:3072 nt
	s_waitcnt vmcnt(22)
	v_lshlrev_b32_e32 v0, 16, v158
	s_waitcnt vmcnt(20)
	v_and_b32_e32 v55, 0xffff0000, v160
	v_and_b32_e32 v50, 0xffff0000, v158
	v_and_b32_e32 v52, 0xffff0000, v159
	v_lshlrev_b32_e32 v51, 16, v159
	v_mul_f32_e32 v53, v50, v50
	v_mul_f32_e32 v54, v52, v52
	v_fmac_f32_e32 v53, v0, v0
	v_fmac_f32_e32 v54, v51, v51
	v_and_b32_e32 v57, 0xffff0000, v161
	v_add_f32_e32 v53, v53, v54
	v_lshlrev_b32_e32 v54, 16, v160
	v_lshlrev_b32_e32 v56, 16, v161
	v_mul_f32_e32 v58, v55, v55
	v_mul_f32_e32 v59, v57, v57
	v_fmac_f32_e32 v58, v54, v54
	v_fmac_f32_e32 v59, v56, v56
	v_add_f32_e32 v58, v58, v59
	s_waitcnt vmcnt(18)
	v_and_b32_e32 v59, 0xffff0000, v162
	v_and_b32_e32 v61, 0xffff0000, v163
	v_add_f32_e32 v53, v53, v58
	v_lshlrev_b32_e32 v58, 16, v162
	v_lshlrev_b32_e32 v60, 16, v163
	v_mul_f32_e32 v62, v59, v59
	v_mul_f32_e32 v63, v61, v61
	v_fmac_f32_e32 v62, v58, v58
	v_fmac_f32_e32 v63, v60, v60
	v_add_f32_e32 v62, v62, v63
	s_waitcnt vmcnt(16)
	v_and_b32_e32 v63, 0xffff0000, v164
	v_and_b32_e32 v65, 0xffff0000, v165
	v_add_f32_e32 v53, v53, v62
	v_lshlrev_b32_e32 v62, 16, v164
	v_lshlrev_b32_e32 v64, 16, v165
	v_mul_f32_e32 v66, v63, v63
	v_mul_f32_e32 v67, v65, v65
	v_fmac_f32_e32 v66, v62, v62
	v_fmac_f32_e32 v67, v64, v64
	v_add_f32_e32 v66, v66, v67
	v_add_f32_e32 v53, v53, v66
	s_nop 1
	v_add_f32_dpp v53, v53, v53 quad_perm:[1,0,3,2] row_mask:0xf bank_mask:0xf bound_ctrl:1
	s_nop 1
	v_add_f32_dpp v53, v53, v53 quad_perm:[2,3,0,1] row_mask:0xf bank_mask:0xf bound_ctrl:1
	s_nop 1
	v_add_f32_dpp v53, v53, v53 row_half_mirror row_mask:0xf bank_mask:0xf bound_ctrl:1
	s_nop 1
	v_add_f32_dpp v53, v53, v53 row_mirror row_mask:0xf bank_mask:0xf bound_ctrl:1
	s_nop 0
	v_readlane_b32 s1, v53, 16
	v_readlane_b32 s6, v53, 48
	v_readlane_b32 s0, v53, 0
	v_readlane_b32 s2, v53, 32
	v_mov_b32_e32 v53, s1
	v_mov_b32_e32 v66, s6
	v_add_f32_e32 v53, s0, v53
	v_add_f32_e32 v66, s2, v66
	v_add_f32_e32 v53, v53, v66
	v_fmamk_f32 v53, v53, 0x3a800000, v188
	v_cmp_gt_f32_e32 vcc, s49, v53
	v_mul_f32_e32 v66, 0x4f800000, v53
	s_nop 0
	v_cndmask_b32_e32 v53, v53, v66, vcc
	v_sqrt_f32_e32 v66, v53
	s_nop 0
	v_add_u32_e32 v67, -1, v66
	v_fma_f32 v68, -v67, v66, v53
	v_cmp_ge_f32_e64 s[0:1], 0, v68
	v_add_u32_e32 v68, 1, v66
	s_nop 0
	v_cndmask_b32_e64 v67, v66, v67, s[0:1]
	v_fma_f32 v66, -v68, v66, v53
	v_cmp_lt_f32_e64 s[0:1], 0, v66
	s_nop 1
	v_cndmask_b32_e64 v66, v67, v68, s[0:1]
	v_mul_f32_e32 v67, 0x37800000, v66
	v_cndmask_b32_e32 v66, v66, v67, vcc
	v_cmp_class_f32_e32 vcc, v53, v189
	s_nop 1
	v_cndmask_b32_e32 v53, v66, v53, vcc
	v_div_scale_f32 v66, s[0:1], v53, v53, 1.0
	v_rcp_f32_e32 v67, v66
	s_nop 0
	v_fma_f32 v68, -v66, v67, 1.0
	v_fmac_f32_e32 v67, v68, v67
	v_div_scale_f32 v68, vcc, 1.0, v53, 1.0
	v_mul_f32_e32 v69, v68, v67
	v_fma_f32 v70, -v66, v69, v68
	v_fmac_f32_e32 v69, v70, v67
	v_fma_f32 v66, -v66, v69, v68
	v_div_fmas_f32 v66, v66, v67, v69
	v_div_fixup_f32 v53, v66, v53, 1.0
	v_mul_f32_e32 v0, v0, v53
	v_mul_f32_e32 v50, v50, v53
	v_mul_f32_e32 v51, v51, v53
	v_mul_f32_e32 v52, v52, v53
	v_fma_f32 v49, v191, v52, v49
	v_fma_f32 v48, v190, v51, v48
	v_fma_f32 v47, v193, v50, v47
	v_fmac_f32_e32 v46, v192, v0
	v_mul_f32_e32 v0, v54, v53
	v_fmac_f32_e32 v42, v196, v0
	v_mul_f32_e32 v212, v55, v53
	v_mul_f32_e32 v213, v56, v53
	v_mul_f32_e32 v214, v57, v53
	v_fma_f32 v45, v195, v214, v45
	v_fma_f32 v44, v194, v213, v44
	v_fma_f32 v43, v197, v212, v43
	v_mul_f32_e32 v0, v58, v53
	v_fmac_f32_e32 v38, v200, v0
	v_mul_f32_e32 v216, v59, v53
	v_mul_f32_e32 v217, v60, v53
	v_mul_f32_e32 v218, v61, v53
	v_fma_f32 v41, v199, v218, v41
	v_fma_f32 v40, v198, v217, v40
	v_fma_f32 v39, v201, v216, v39
	v_mul_f32_e32 v0, v62, v53
	v_fmac_f32_e32 v34, v204, v0
	v_mul_f32_e32 v220, v63, v53
	v_mul_f32_e32 v221, v64, v53
	v_mul_f32_e32 v222, v65, v53
	v_fma_f32 v37, v203, v222, v37
	v_fma_f32 v36, v202, v221, v36
	v_fma_f32 v35, v205, v220, v35
	s_waitcnt vmcnt(22)
	v_lshlrev_b32_e32 v0, 16, v110
	s_waitcnt vmcnt(20)
	v_and_b32_e32 v55, 0xffff0000, v108
	v_and_b32_e32 v50, 0xffff0000, v110
	v_and_b32_e32 v52, 0xffff0000, v111
	v_lshlrev_b32_e32 v51, 16, v111
	v_mul_f32_e32 v53, v50, v50
	v_mul_f32_e32 v54, v52, v52
	v_fmac_f32_e32 v53, v0, v0
	v_fmac_f32_e32 v54, v51, v51
	v_and_b32_e32 v57, 0xffff0000, v109
	v_add_f32_e32 v53, v53, v54
	v_lshlrev_b32_e32 v54, 16, v108
	v_lshlrev_b32_e32 v56, 16, v109
	v_mul_f32_e32 v58, v55, v55
	v_mul_f32_e32 v59, v57, v57
	v_fmac_f32_e32 v58, v54, v54
	v_fmac_f32_e32 v59, v56, v56
	v_add_f32_e32 v58, v58, v59
	s_waitcnt vmcnt(18)
	v_and_b32_e32 v59, 0xffff0000, v106
	v_and_b32_e32 v61, 0xffff0000, v107
	v_add_f32_e32 v53, v53, v58
	v_lshlrev_b32_e32 v58, 16, v106
	v_lshlrev_b32_e32 v60, 16, v107
	v_mul_f32_e32 v62, v59, v59
	v_mul_f32_e32 v63, v61, v61
	v_fmac_f32_e32 v62, v58, v58
	v_fmac_f32_e32 v63, v60, v60
	v_add_f32_e32 v62, v62, v63
	s_waitcnt vmcnt(16)
	v_and_b32_e32 v63, 0xffff0000, v102
	v_and_b32_e32 v65, 0xffff0000, v103
	v_add_f32_e32 v53, v53, v62
	v_lshlrev_b32_e32 v62, 16, v102
	v_lshlrev_b32_e32 v64, 16, v103
	v_mul_f32_e32 v66, v63, v63
	v_mul_f32_e32 v67, v65, v65
	v_fmac_f32_e32 v66, v62, v62
	v_fmac_f32_e32 v67, v64, v64
	v_add_f32_e32 v66, v66, v67
	v_add_f32_e32 v53, v53, v66
	s_nop 1
	v_add_f32_dpp v53, v53, v53 quad_perm:[1,0,3,2] row_mask:0xf bank_mask:0xf bound_ctrl:1
	s_nop 1
	v_add_f32_dpp v53, v53, v53 quad_perm:[2,3,0,1] row_mask:0xf bank_mask:0xf bound_ctrl:1
	s_nop 1
	v_add_f32_dpp v53, v53, v53 row_half_mirror row_mask:0xf bank_mask:0xf bound_ctrl:1
	s_nop 1
	v_add_f32_dpp v53, v53, v53 row_mirror row_mask:0xf bank_mask:0xf bound_ctrl:1
	s_nop 0
	v_readlane_b32 s1, v53, 16
	v_readlane_b32 s6, v53, 48
	v_readlane_b32 s0, v53, 0
	v_readlane_b32 s2, v53, 32
	v_mov_b32_e32 v53, s1
	v_mov_b32_e32 v66, s6
	v_add_f32_e32 v53, s0, v53
	v_add_f32_e32 v66, s2, v66
	v_add_f32_e32 v53, v53, v66
	v_fmamk_f32 v53, v53, 0x3a800000, v188
	v_cmp_gt_f32_e32 vcc, s49, v53
	v_mul_f32_e32 v66, 0x4f800000, v53
	s_nop 0
	v_cndmask_b32_e32 v53, v53, v66, vcc
	v_sqrt_f32_e32 v66, v53
	s_nop 0
	v_add_u32_e32 v67, -1, v66
	v_fma_f32 v68, -v67, v66, v53
	v_cmp_ge_f32_e64 s[0:1], 0, v68
	v_add_u32_e32 v68, 1, v66
	s_nop 0
	v_cndmask_b32_e64 v67, v66, v67, s[0:1]
	v_fma_f32 v66, -v68, v66, v53
	v_cmp_lt_f32_e64 s[0:1], 0, v66
	s_nop 1
	v_cndmask_b32_e64 v66, v67, v68, s[0:1]
	v_mul_f32_e32 v67, 0x37800000, v66
	v_cndmask_b32_e32 v66, v66, v67, vcc
	v_cmp_class_f32_e32 vcc, v53, v189
	s_nop 1
	v_cndmask_b32_e32 v53, v66, v53, vcc
	v_div_scale_f32 v66, s[0:1], v53, v53, 1.0
	v_rcp_f32_e32 v67, v66
	s_nop 0
	v_fma_f32 v68, -v66, v67, 1.0
	v_fmac_f32_e32 v67, v68, v67
	v_div_scale_f32 v68, vcc, 1.0, v53, 1.0
	v_mul_f32_e32 v69, v68, v67
	v_fma_f32 v70, -v66, v69, v68
	v_fmac_f32_e32 v69, v70, v67
	v_fma_f32 v66, -v66, v69, v68
	v_div_fmas_f32 v66, v66, v67, v69
	v_div_fixup_f32 v53, v66, v53, 1.0
	v_mul_f32_e32 v0, v0, v53
	v_mul_f32_e32 v50, v50, v53
	v_mul_f32_e32 v51, v51, v53
	v_mul_f32_e32 v52, v52, v53
	v_fma_f32 v49, v3, v52, v49
	v_fma_f32 v48, v2, v51, v48
	v_fma_f32 v47, v5, v50, v47
	v_fmac_f32_e32 v46, v4, v0
	global_store_dwordx4 v[90:91], v[46:49], off nt
	v_mul_f32_e32 v0, v54, v53
	v_fmac_f32_e32 v42, v8, v0
	v_mul_f32_e32 v46, v55, v53
	v_mul_f32_e32 v47, v56, v53
	v_mul_f32_e32 v48, v57, v53
	v_fma_f32 v45, v7, v48, v45
	v_fma_f32 v44, v6, v47, v44
	v_fma_f32 v43, v9, v46, v43
	global_store_dwordx4 v[90:91], v[42:45], off offset:1024 nt
	v_mul_f32_e32 v0, v58, v53
	v_fmac_f32_e32 v38, v12, v0
	v_mul_f32_e32 v42, v59, v53
	v_mul_f32_e32 v43, v60, v53
	v_mul_f32_e32 v44, v61, v53
	v_fma_f32 v41, v11, v44, v41
	v_fma_f32 v40, v10, v43, v40
	v_fma_f32 v39, v13, v42, v39
	global_store_dwordx4 v[90:91], v[38:41], off offset:2048 nt
	v_mul_f32_e32 v0, v62, v53
	v_fmac_f32_e32 v34, v16, v0
	v_mul_f32_e32 v38, v63, v53
	v_mul_f32_e32 v39, v64, v53
	v_mul_f32_e32 v40, v65, v53
	v_fma_f32 v37, v15, v40, v37
	v_fma_f32 v36, v14, v39, v36
	v_fma_f32 v35, v17, v38, v35
	global_store_dwordx4 v[90:91], v[34:37], off offset:3072 nt
	s_waitcnt vmcnt(18)
	v_lshlrev_b32_e32 v0, 16, v166
	s_waitcnt vmcnt(16)
	v_and_b32_e32 v39, 0xffff0000, v168
	v_and_b32_e32 v34, 0xffff0000, v166
	v_and_b32_e32 v36, 0xffff0000, v167
	v_lshlrev_b32_e32 v35, 16, v167
	v_mul_f32_e32 v37, v34, v34
	v_mul_f32_e32 v38, v36, v36
	v_fmac_f32_e32 v37, v0, v0
	v_fmac_f32_e32 v38, v35, v35
	v_and_b32_e32 v41, 0xffff0000, v169
	v_add_f32_e32 v37, v37, v38
	v_lshlrev_b32_e32 v38, 16, v168
	v_lshlrev_b32_e32 v40, 16, v169
	v_mul_f32_e32 v42, v39, v39
	v_mul_f32_e32 v43, v41, v41
	v_fmac_f32_e32 v42, v38, v38
	v_fmac_f32_e32 v43, v40, v40
	v_add_f32_e32 v42, v42, v43
	s_waitcnt vmcnt(14)
	v_and_b32_e32 v43, 0xffff0000, v170
	v_and_b32_e32 v45, 0xffff0000, v171
	v_add_f32_e32 v37, v37, v42
	v_lshlrev_b32_e32 v42, 16, v170
	v_lshlrev_b32_e32 v44, 16, v171
	v_mul_f32_e32 v46, v43, v43
	v_mul_f32_e32 v47, v45, v45
	v_fmac_f32_e32 v46, v42, v42
	v_fmac_f32_e32 v47, v44, v44
	v_add_f32_e32 v46, v46, v47
	s_waitcnt vmcnt(12)
	v_and_b32_e32 v47, 0xffff0000, v172
	v_and_b32_e32 v49, 0xffff0000, v173
	v_add_f32_e32 v37, v37, v46
	v_lshlrev_b32_e32 v46, 16, v172
	v_lshlrev_b32_e32 v48, 16, v173
	v_mul_f32_e32 v50, v47, v47
	v_mul_f32_e32 v51, v49, v49
	v_fmac_f32_e32 v50, v46, v46
	v_fmac_f32_e32 v51, v48, v48
	v_add_f32_e32 v50, v50, v51
	v_add_f32_e32 v37, v37, v50
	s_nop 1
	v_add_f32_dpp v37, v37, v37 quad_perm:[1,0,3,2] row_mask:0xf bank_mask:0xf bound_ctrl:1
	s_nop 1
	v_add_f32_dpp v37, v37, v37 quad_perm:[2,3,0,1] row_mask:0xf bank_mask:0xf bound_ctrl:1
	s_nop 1
	v_add_f32_dpp v37, v37, v37 row_half_mirror row_mask:0xf bank_mask:0xf bound_ctrl:1
	s_nop 1
	v_add_f32_dpp v37, v37, v37 row_mirror row_mask:0xf bank_mask:0xf bound_ctrl:1
	s_nop 0
	v_readlane_b32 s1, v37, 16
	v_readlane_b32 s6, v37, 48
	v_readlane_b32 s0, v37, 0
	v_readlane_b32 s2, v37, 32
	v_mov_b32_e32 v37, s1
	v_mov_b32_e32 v50, s6
	v_add_f32_e32 v37, s0, v37
	v_add_f32_e32 v50, s2, v50
	v_add_f32_e32 v37, v37, v50
	v_fmamk_f32 v37, v37, 0x3a800000, v188
	v_cmp_gt_f32_e32 vcc, s49, v37
	v_mul_f32_e32 v50, 0x4f800000, v37
	s_nop 0
	v_cndmask_b32_e32 v37, v37, v50, vcc
	v_sqrt_f32_e32 v50, v37
	s_nop 0
	v_add_u32_e32 v51, -1, v50
	v_fma_f32 v52, -v51, v50, v37
	v_cmp_ge_f32_e64 s[0:1], 0, v52
	v_add_u32_e32 v52, 1, v50
	s_nop 0
	v_cndmask_b32_e64 v51, v50, v51, s[0:1]
	v_fma_f32 v50, -v52, v50, v37
	v_cmp_lt_f32_e64 s[0:1], 0, v50
	s_nop 1
	v_cndmask_b32_e64 v50, v51, v52, s[0:1]
	v_mul_f32_e32 v51, 0x37800000, v50
	v_cndmask_b32_e32 v50, v50, v51, vcc
	v_cmp_class_f32_e32 vcc, v37, v189
	s_nop 1
	v_cndmask_b32_e32 v37, v50, v37, vcc
	v_div_scale_f32 v50, s[0:1], v37, v37, 1.0
	v_rcp_f32_e32 v51, v50
	s_nop 0
	v_fma_f32 v52, -v50, v51, 1.0
	v_fmac_f32_e32 v51, v52, v51
	v_div_scale_f32 v52, vcc, 1.0, v37, 1.0
	v_mul_f32_e32 v53, v52, v51
	v_fma_f32 v54, -v50, v53, v52
	v_fmac_f32_e32 v53, v54, v51
	v_fma_f32 v50, -v50, v53, v52
	v_div_fmas_f32 v50, v50, v51, v53
	v_div_fixup_f32 v37, v50, v37, 1.0
	v_mul_f32_e32 v0, v0, v37
	v_mul_f32_e32 v34, v34, v37
	v_mul_f32_e32 v35, v35, v37
	v_mul_f32_e32 v36, v36, v37
	v_fma_f32 v33, v191, v36, v33
	v_fma_f32 v32, v190, v35, v32
	v_fma_f32 v31, v193, v34, v31
	v_fmac_f32_e32 v30, v192, v0
	v_mul_f32_e32 v0, v38, v37
	v_fmac_f32_e32 v26, v196, v0
	v_mul_f32_e32 v212, v39, v37
	v_mul_f32_e32 v213, v40, v37
	v_mul_f32_e32 v214, v41, v37
	v_fma_f32 v29, v195, v214, v29
	v_fma_f32 v28, v194, v213, v28
	v_fma_f32 v27, v197, v212, v27
	v_mul_f32_e32 v0, v42, v37
	v_fmac_f32_e32 v22, v200, v0
	v_mul_f32_e32 v216, v43, v37
	v_mul_f32_e32 v217, v44, v37
	v_mul_f32_e32 v218, v45, v37
	v_fma_f32 v25, v199, v218, v25
	v_fma_f32 v24, v198, v217, v24
	v_fma_f32 v23, v201, v216, v23
	v_mul_f32_e32 v0, v46, v37
	v_cmp_lt_i32_e32 vcc, s61, v120
	v_mul_f32_e32 v220, v47, v37
	v_mul_f32_e32 v221, v48, v37
	v_mul_f32_e32 v222, v49, v37
	v_fma_f32 v21, v203, v222, v21
	v_fma_f32 v20, v202, v221, v20
	v_fma_f32 v19, v205, v220, v19
	v_fmac_f32_e32 v18, v204, v0
	s_or_b64 s[34:35], vcc, s[34:35]
	s_waitcnt vmcnt(18)
	v_lshlrev_b32_e32 v0, 16, v100
	s_waitcnt vmcnt(16)
	v_and_b32_e32 v39, 0xffff0000, v98
	v_and_b32_e32 v34, 0xffff0000, v100
	v_and_b32_e32 v36, 0xffff0000, v101
	v_lshlrev_b32_e32 v35, 16, v101
	v_mul_f32_e32 v37, v34, v34
	v_mul_f32_e32 v38, v36, v36
	v_fmac_f32_e32 v37, v0, v0
	v_fmac_f32_e32 v38, v35, v35
	v_and_b32_e32 v41, 0xffff0000, v99
	v_add_f32_e32 v37, v37, v38
	v_lshlrev_b32_e32 v38, 16, v98
	v_lshlrev_b32_e32 v40, 16, v99
	v_mul_f32_e32 v42, v39, v39
	v_mul_f32_e32 v43, v41, v41
	v_fmac_f32_e32 v42, v38, v38
	v_fmac_f32_e32 v43, v40, v40
	v_add_f32_e32 v42, v42, v43
	s_waitcnt vmcnt(14)
	v_and_b32_e32 v43, 0xffff0000, v96
	v_and_b32_e32 v45, 0xffff0000, v97
	v_add_f32_e32 v37, v37, v42
	v_lshlrev_b32_e32 v42, 16, v96
	v_lshlrev_b32_e32 v44, 16, v97
	v_mul_f32_e32 v46, v43, v43
	v_mul_f32_e32 v47, v45, v45
	v_fmac_f32_e32 v46, v42, v42
	v_fmac_f32_e32 v47, v44, v44
	v_add_f32_e32 v46, v46, v47
	s_waitcnt vmcnt(12)
	v_and_b32_e32 v47, 0xffff0000, v92
	v_and_b32_e32 v49, 0xffff0000, v93
	v_add_f32_e32 v37, v37, v46
	v_lshlrev_b32_e32 v46, 16, v92
	v_lshlrev_b32_e32 v48, 16, v93
	v_mul_f32_e32 v50, v47, v47
	v_mul_f32_e32 v51, v49, v49
	v_fmac_f32_e32 v50, v46, v46
	v_fmac_f32_e32 v51, v48, v48
	v_add_f32_e32 v50, v50, v51
	v_add_f32_e32 v37, v37, v50
	s_nop 1
	v_add_f32_dpp v37, v37, v37 quad_perm:[1,0,3,2] row_mask:0xf bank_mask:0xf bound_ctrl:1
	s_nop 1
	v_add_f32_dpp v37, v37, v37 quad_perm:[2,3,0,1] row_mask:0xf bank_mask:0xf bound_ctrl:1
	s_nop 1
	v_add_f32_dpp v37, v37, v37 row_half_mirror row_mask:0xf bank_mask:0xf bound_ctrl:1
	s_nop 1
	v_add_f32_dpp v37, v37, v37 row_mirror row_mask:0xf bank_mask:0xf bound_ctrl:1
	s_nop 0
	v_readlane_b32 s1, v37, 16
	v_readlane_b32 s6, v37, 48
	v_readlane_b32 s0, v37, 0
	v_readlane_b32 s2, v37, 32
	v_mov_b32_e32 v37, s1
	v_mov_b32_e32 v50, s6
	v_add_f32_e32 v37, s0, v37
	v_add_f32_e32 v50, s2, v50
	v_add_f32_e32 v37, v37, v50
	v_fmamk_f32 v37, v37, 0x3a800000, v188
	v_cmp_gt_f32_e32 vcc, s49, v37
	v_mul_f32_e32 v50, 0x4f800000, v37
	s_nop 0
	v_cndmask_b32_e32 v37, v37, v50, vcc
	v_sqrt_f32_e32 v50, v37
	s_nop 0
	v_add_u32_e32 v51, -1, v50
	v_fma_f32 v52, -v51, v50, v37
	v_cmp_ge_f32_e64 s[0:1], 0, v52
	v_add_u32_e32 v52, 1, v50
	s_nop 0
	v_cndmask_b32_e64 v51, v50, v51, s[0:1]
	v_fma_f32 v50, -v52, v50, v37
	v_cmp_lt_f32_e64 s[0:1], 0, v50
	s_nop 1
	v_cndmask_b32_e64 v50, v51, v52, s[0:1]
	v_mul_f32_e32 v51, 0x37800000, v50
	v_cndmask_b32_e32 v50, v50, v51, vcc
	v_cmp_class_f32_e32 vcc, v37, v189
	s_nop 1
	v_cndmask_b32_e32 v37, v50, v37, vcc
	v_div_scale_f32 v50, s[0:1], v37, v37, 1.0
	v_rcp_f32_e32 v51, v50
	s_nop 0
	v_fma_f32 v52, -v50, v51, 1.0
	v_fmac_f32_e32 v51, v52, v51
	v_div_scale_f32 v52, vcc, 1.0, v37, 1.0
	v_mul_f32_e32 v53, v52, v51
	v_fma_f32 v54, -v50, v53, v52
	v_fmac_f32_e32 v53, v54, v51
	v_fma_f32 v50, -v50, v53, v52
	v_div_fmas_f32 v50, v50, v51, v53
	v_div_fixup_f32 v37, v50, v37, 1.0
	v_mul_f32_e32 v0, v0, v37
	v_mul_f32_e32 v34, v34, v37
	v_mul_f32_e32 v35, v35, v37
	v_mul_f32_e32 v36, v36, v37
	v_fma_f32 v33, v3, v36, v33
	v_fma_f32 v32, v2, v35, v32
	v_fma_f32 v31, v5, v34, v31
	v_fmac_f32_e32 v30, v4, v0
	global_store_dwordx4 v[88:89], v[30:33], off nt
	v_mul_f32_e32 v0, v38, v37
	v_fmac_f32_e32 v26, v8, v0
	v_mul_f32_e32 v30, v39, v37
	v_mul_f32_e32 v31, v40, v37
	v_mul_f32_e32 v32, v41, v37
	v_fma_f32 v29, v7, v32, v29
	v_fma_f32 v28, v6, v31, v28
	v_fma_f32 v27, v9, v30, v27
	global_store_dwordx4 v[88:89], v[26:29], off offset:1024 nt
	v_mul_f32_e32 v0, v42, v37
	v_fmac_f32_e32 v22, v12, v0
	v_mul_f32_e32 v26, v43, v37
	v_mul_f32_e32 v27, v44, v37
	v_mul_f32_e32 v28, v45, v37
	v_fma_f32 v25, v11, v28, v25
	v_fma_f32 v24, v10, v27, v24
	v_fma_f32 v23, v13, v26, v23
	global_store_dwordx4 v[88:89], v[22:25], off offset:2048 nt
	v_mul_f32_e32 v0, v46, v37
	v_cmp_lt_i32_e32 vcc, s61, v120
	v_mul_f32_e32 v22, v47, v37
	v_mul_f32_e32 v23, v48, v37
	v_mul_f32_e32 v24, v49, v37
	v_fma_f32 v21, v15, v24, v21
	v_fma_f32 v20, v14, v23, v20
	v_fma_f32 v19, v17, v22, v19
	v_fmac_f32_e32 v18, v16, v0
	s_or_b64 s[34:35], vcc, s[34:35]
	global_store_dwordx4 v[88:89], v[18:21], off offset:3072 nt
	s_andn2_b64 exec, exec, s[34:35]
	s_cbranch_execnz .LBB0_28
